# in-proj epilogue stores sc1 nt, out-proj residual x loads nt (streaming traffic kept out of the caches that hold the GEMM operands)
# speedup vs baseline: 1.0371x; 1.0055x over previous
; __device__ __forceinline__ unsigned pk2(float lo, float hi) { f32x2_t v = {lo, hi}; bf16x2_t b = __builtin_convertvector(v, bf16x2_t); return __builtin_bit_cast(unsigned, b); }
; __device__ __forceinline__ float silu_f(float v) { return v * __builtin_amdgcn_rcpf(1.f + __builtin_amdgcn_exp2f(-v * LOG2E)); }
; template <int CTRL> __device__ __forceinline__ unsigned dpp_mov(unsigned v) { return (unsigned)__builtin_amdgcn_update_dpp(0, (int)v, CTRL, 0xF, 0xF, true); }
;     __device__ __forceinline__ void operator()(const pg8::f32x4 (&acc)[2][2][4][2], const pg8::Unit& u, int wr, int wc, int fr, int fq) const {
;     ...
;                 pg8::f32x4 a0 = acc[ai][0][m][0], a1 = acc[ai][0][m][1], b0 = acc[ai][1][m][0], b1 = acc[ai][1][m][1];
;                 if (act) {
; #pragma unroll
;                     for (int e = 0; e < 4; ++e) { a0[e] = silu_f(a0[e]); a1[e] = silu_f(a1[e]); b0[e] = silu_f(b0[e]); b1[e] = silu_f(b1[e]); } }
;                 u32x4 A, B; A.x = pk2(a0[0], a0[1]); A.y = pk2(a0[2], a0[3]); A.z = pk2(a1[0], a1[1]); A.w = pk2(a1[2], a1[3]);
;                 B.x = pk2(b0[0], b0[1]); B.y = pk2(b0[2], b0[3]); B.z = pk2(b1[0], b1[1]); B.w = pk2(b1[2], b1[3]);
;                 u32x4 snd, rcv;
; #pragma unroll
;                 for (int e = 0; e < 4; ++e) { snd[e] = hi8 ? A[e] : B[e]; rcv[e] = dpp_mov<0x128>(snd[e]); }
;                 u32x4 d1, d2;
; #pragma unroll
;                 for (int e = 0; e < 4; ++e) { d1[e] = hi8 ? rcv[e] : A[e]; d2[e] = hi8 ? B[e] : rcv[e]; }
;                 const int row1 = rbase + ai * 128 + m * 16, row2 = row1 + 8;
;                 if (qkv) {
;                     const int bb = row1 >> 13, t1 = row1 & (SEQ - 1), t2 = row2 & (SEQ - 1);
;                     const int p1 = (t1 & dmask) * Lc + (t1 >> dsh), p2 = (t2 & dmask) * Lc + (t2 >> dsh);
;                     bf16_t* hb = base + (size_t)bb * 24 * SEQ * 64 + ecol;
;                     *(u32x4*)(hb + (size_t)p1 * 64) = d1; *(u32x4*)(hb + (size_t)p2 * 64) = d2;
.Lp1_nn0:
	s_lshl_b32 s6, s6, 8
	s_add_i32 s62, s6, s74
	s_lshl_b64 s[6:7], s[8:9], 1
	s_add_u32 s6, s60, s6
	s_addc_u32 s7, s61, s7
	s_sub_i32 s21, 13, s17
	v_lshl_add_u64 v[140:141], s[6:7], 0, v[132:133]
	s_and_b64 s[6:7], s[58:59], exec
	s_cselect_b32 s8, 9, 10
	s_ashr_i32 s6, s62, 13
	v_cvt_pk_bf16_f32 v124, v124, v125
	v_cvt_pk_bf16_f32 v125, v126, v127
	v_cvt_pk_bf16_f32 v120, v120, v121
	v_cvt_pk_bf16_f32 v121, v122, v123
	v_cvt_pk_bf16_f32 v117, v116, v117
	v_cvt_pk_bf16_f32 v118, v118, v119
	v_cvt_pk_bf16_f32 v119, v112, v113
	v_cvt_pk_bf16_f32 v115, v114, v115
	s_mul_i32 s6, s6, 24
	v_cndmask_b32_e64 v112, v124, v117, s[0:1]
	v_cndmask_b32_e64 v113, v125, v118, s[0:1]
	v_cndmask_b32_e64 v114, v120, v119, s[0:1]
	v_cndmask_b32_e64 v116, v121, v115, s[0:1]
	s_ashr_i32 s7, s6, 31
	v_mov_b32_dpp v112, v112 row_ror:8 row_mask:0xf bank_mask:0xf bound_ctrl:1
	v_mov_b32_dpp v113, v113 row_ror:8 row_mask:0xf bank_mask:0xf bound_ctrl:1
	v_mov_b32_dpp v114, v114 row_ror:8 row_mask:0xf bank_mask:0xf bound_ctrl:1
	v_mov_b32_dpp v122, v116 row_ror:8 row_mask:0xf bank_mask:0xf bound_ctrl:1
	s_lshl_b64 s[6:7], s[6:7], 20
	v_or_b32_e32 v142, s62, v147
	v_cndmask_b32_e64 v116, v112, v124, s[0:1]
	v_cndmask_b32_e64 v112, v117, v112, s[0:1]
	v_cndmask_b32_e64 v117, v113, v125, s[0:1]
	v_cndmask_b32_e64 v113, v118, v113, s[0:1]
	v_cndmask_b32_e64 v118, v114, v120, s[0:1]
	v_cndmask_b32_e64 v114, v119, v114, s[0:1]
	v_cndmask_b32_e64 v119, v122, v121, s[0:1]
	v_cndmask_b32_e64 v121, 0, 1, s[28:29]
	v_lshl_add_u64 v[144:145], v[140:141], 0, s[6:7]
	v_cndmask_b32_e64 v115, v115, v122, s[0:1]
	v_or_b32_e32 v120, 8, v142
	v_cmp_ne_u32_e64 s[6:7], 1, v121
	s_andn2_b64 vcc, exec, s[28:29]
	s_mov_b64 s[28:29], -1
	s_cbranch_vccnz .LBB0_206
	v_and_b32_e32 v121, 0x1fc7, v142
	v_lshlrev_b32_e32 v123, s21, v142
	v_and_b32_e32 v122, 0x1fcf, v120
	v_and_b32_e32 v123, 0x1ffe, v123
	v_lshrrev_b32_e32 v121, s17, v121
	v_lshlrev_b32_e32 v124, s21, v120
	v_lshrrev_b32_e32 v125, s17, v122
	v_add_lshl_u32 v122, v123, v121, 7
	v_mov_b32_e32 v123, v133
	v_and_b32_e32 v124, 0x1ffe, v124
	v_lshl_add_u64 v[122:123], v[144:145], 0, v[122:123]
	global_store_dwordx4 v[122:123], v[116:119], off sc1 nt
	v_add_lshl_u32 v122, v124, v125, 7
	v_mov_b32_e32 v123, v133
	v_lshl_add_u64 v[122:123], v[144:145], 0, v[122:123]
	global_store_dwordx4 v[122:123], v[112:115], off sc1 nt
	s_cbranch_execz .LBB0_207

; __device__ __forceinline__ unsigned pk2(float lo, float hi) { f32x2_t v = {lo, hi}; bf16x2_t b = __builtin_convertvector(v, bf16x2_t); return __builtin_bit_cast(unsigned, b); }
; __device__ __forceinline__ float silu_f(float v) { return v * __builtin_amdgcn_rcpf(1.f + __builtin_amdgcn_exp2f(-v * LOG2E)); }
; template <int CTRL> __device__ __forceinline__ unsigned dpp_mov(unsigned v) { return (unsigned)__builtin_amdgcn_update_dpp(0, (int)v, CTRL, 0xF, 0xF, true); }
;     __device__ __forceinline__ void operator()(const pg8::f32x4 (&acc)[2][2][4][2], const pg8::Unit& u, int wr, int wc, int fr, int fq) const {
;     ...
;                 pg8::f32x4 a0 = acc[ai][0][m][0], a1 = acc[ai][0][m][1], b0 = acc[ai][1][m][0], b1 = acc[ai][1][m][1];
;                 if (act) {
; #pragma unroll
;                     for (int e = 0; e < 4; ++e) { a0[e] = silu_f(a0[e]); a1[e] = silu_f(a1[e]); b0[e] = silu_f(b0[e]); b1[e] = silu_f(b1[e]); } }
;                 u32x4 A, B; A.x = pk2(a0[0], a0[1]); A.y = pk2(a0[2], a0[3]); A.z = pk2(a1[0], a1[1]); A.w = pk2(a1[2], a1[3]);
;                 B.x = pk2(b0[0], b0[1]); B.y = pk2(b0[2], b0[3]); B.z = pk2(b1[0], b1[1]); B.w = pk2(b1[2], b1[3]);
;                 u32x4 snd, rcv;
; #pragma unroll
;                 for (int e = 0; e < 4; ++e) { snd[e] = hi8 ? A[e] : B[e]; rcv[e] = dpp_mov<0x128>(snd[e]); }
;                 u32x4 d1, d2;
; #pragma unroll
;                 for (int e = 0; e < 4; ++e) { d1[e] = hi8 ? rcv[e] : A[e]; d2[e] = hi8 ? B[e] : rcv[e]; }
;                 const int row1 = rbase + ai * 128 + m * 16, row2 = row1 + 8;
;                 if (qkv) {
;                     const int bb = row1 >> 13, t1 = row1 & (SEQ - 1), t2 = row2 & (SEQ - 1);
;                     const int p1 = (t1 & dmask) * Lc + (t1 >> dsh), p2 = (t2 & dmask) * Lc + (t2 >> dsh);
;                     bf16_t* hb = base + (size_t)bb * 24 * SEQ * 64 + ecol;
;                     *(u32x4*)(hb + (size_t)p1 * 64) = d1; *(u32x4*)(hb + (size_t)p2 * 64) = d2;
.Lp1_nn1:
	v_cvt_pk_bf16_f32 v108, v108, v109
	v_cvt_pk_bf16_f32 v109, v110, v111
	v_cvt_pk_bf16_f32 v104, v104, v105
	v_cvt_pk_bf16_f32 v105, v106, v107
	v_cvt_pk_bf16_f32 v101, v100, v101
	v_cvt_pk_bf16_f32 v102, v102, v103
	v_cvt_pk_bf16_f32 v103, v96, v97
	v_cvt_pk_bf16_f32 v99, v98, v99
	v_cndmask_b32_e64 v96, v108, v101, s[0:1]
	v_cndmask_b32_e64 v97, v109, v102, s[0:1]
	v_cndmask_b32_e64 v98, v104, v103, s[0:1]
	v_cndmask_b32_e64 v100, v105, v99, s[0:1]
	v_mov_b32_dpp v96, v96 row_ror:8 row_mask:0xf bank_mask:0xf bound_ctrl:1
	v_mov_b32_dpp v97, v97 row_ror:8 row_mask:0xf bank_mask:0xf bound_ctrl:1
	v_mov_b32_dpp v98, v98 row_ror:8 row_mask:0xf bank_mask:0xf bound_ctrl:1
	v_mov_b32_dpp v106, v100 row_ror:8 row_mask:0xf bank_mask:0xf bound_ctrl:1
	v_cndmask_b32_e64 v100, v96, v108, s[0:1]
	v_cndmask_b32_e64 v96, v101, v96, s[0:1]
	v_cndmask_b32_e64 v101, v97, v109, s[0:1]
	v_cndmask_b32_e64 v97, v102, v97, s[0:1]
	v_cndmask_b32_e64 v102, v98, v104, s[0:1]
	v_cndmask_b32_e64 v98, v103, v98, s[0:1]
	v_cndmask_b32_e64 v103, v106, v105, s[0:1]
	v_cndmask_b32_e64 v99, v99, v106, s[0:1]
	v_or_b32_e32 v106, 16, v142
	v_or_b32_e32 v104, 24, v142
	s_and_b64 vcc, exec, s[6:7]
	s_mov_b64 s[28:29], -1
	s_cbranch_vccnz .LBB0_208
	v_and_b32_e32 v105, 0x1fd7, v106
	v_lshlrev_b32_e32 v108, s21, v105
	v_and_b32_e32 v108, 0x1ffe, v108
	v_lshrrev_b32_e32 v105, s17, v105
	v_lshlrev_b32_e32 v109, s21, v104
	v_and_b32_e32 v107, 0x1fdf, v104
	v_and_b32_e32 v110, 0x1ffe, v109
	v_add_lshl_u32 v108, v108, v105, 7
	v_mov_b32_e32 v109, v133
	v_lshrrev_b32_e32 v107, s17, v107
	v_lshl_add_u64 v[108:109], v[144:145], 0, v[108:109]
	global_store_dwordx4 v[108:109], v[100:103], off sc1 nt
	v_add_lshl_u32 v108, v110, v107, 7
	v_mov_b32_e32 v109, v133
	v_lshl_add_u64 v[108:109], v[144:145], 0, v[108:109]
	global_store_dwordx4 v[108:109], v[96:99], off sc1 nt
	s_cbranch_execz .LBB0_209

; __device__ __forceinline__ unsigned pk2(float lo, float hi) { f32x2_t v = {lo, hi}; bf16x2_t b = __builtin_convertvector(v, bf16x2_t); return __builtin_bit_cast(unsigned, b); }
; __device__ __forceinline__ float silu_f(float v) { return v * __builtin_amdgcn_rcpf(1.f + __builtin_amdgcn_exp2f(-v * LOG2E)); }
; template <int CTRL> __device__ __forceinline__ unsigned dpp_mov(unsigned v) { return (unsigned)__builtin_amdgcn_update_dpp(0, (int)v, CTRL, 0xF, 0xF, true); }
;     __device__ __forceinline__ void operator()(const pg8::f32x4 (&acc)[2][2][4][2], const pg8::Unit& u, int wr, int wc, int fr, int fq) const {
;     ...
;                 pg8::f32x4 a0 = acc[ai][0][m][0], a1 = acc[ai][0][m][1], b0 = acc[ai][1][m][0], b1 = acc[ai][1][m][1];
;                 if (act) {
; #pragma unroll
;                     for (int e = 0; e < 4; ++e) { a0[e] = silu_f(a0[e]); a1[e] = silu_f(a1[e]); b0[e] = silu_f(b0[e]); b1[e] = silu_f(b1[e]); } }
;                 u32x4 A, B; A.x = pk2(a0[0], a0[1]); A.y = pk2(a0[2], a0[3]); A.z = pk2(a1[0], a1[1]); A.w = pk2(a1[2], a1[3]);
;                 B.x = pk2(b0[0], b0[1]); B.y = pk2(b0[2], b0[3]); B.z = pk2(b1[0], b1[1]); B.w = pk2(b1[2], b1[3]);
;                 u32x4 snd, rcv;
; #pragma unroll
;                 for (int e = 0; e < 4; ++e) { snd[e] = hi8 ? A[e] : B[e]; rcv[e] = dpp_mov<0x128>(snd[e]); }
;                 u32x4 d1, d2;
; #pragma unroll
;                 for (int e = 0; e < 4; ++e) { d1[e] = hi8 ? rcv[e] : A[e]; d2[e] = hi8 ? B[e] : rcv[e]; }
;                 const int row1 = rbase + ai * 128 + m * 16, row2 = row1 + 8;
;                 if (qkv) {
;                     const int bb = row1 >> 13, t1 = row1 & (SEQ - 1), t2 = row2 & (SEQ - 1);
;                     const int p1 = (t1 & dmask) * Lc + (t1 >> dsh), p2 = (t2 & dmask) * Lc + (t2 >> dsh);
;                     bf16_t* hb = base + (size_t)bb * 24 * SEQ * 64 + ecol;
;                     *(u32x4*)(hb + (size_t)p1 * 64) = d1; *(u32x4*)(hb + (size_t)p2 * 64) = d2;
.Lp1_nn2:
	v_cvt_pk_bf16_f32 v92, v92, v93
	v_cvt_pk_bf16_f32 v93, v94, v95
	v_cvt_pk_bf16_f32 v88, v88, v89
	v_cvt_pk_bf16_f32 v89, v90, v91
	v_cvt_pk_bf16_f32 v85, v84, v85
	v_cvt_pk_bf16_f32 v86, v86, v87
	v_cvt_pk_bf16_f32 v87, v80, v81
	v_cvt_pk_bf16_f32 v83, v82, v83
	v_cndmask_b32_e64 v80, v92, v85, s[0:1]
	v_cndmask_b32_e64 v81, v93, v86, s[0:1]
	v_cndmask_b32_e64 v82, v88, v87, s[0:1]
	v_cndmask_b32_e64 v84, v89, v83, s[0:1]
	v_mov_b32_dpp v80, v80 row_ror:8 row_mask:0xf bank_mask:0xf bound_ctrl:1
	v_mov_b32_dpp v81, v81 row_ror:8 row_mask:0xf bank_mask:0xf bound_ctrl:1
	v_mov_b32_dpp v82, v82 row_ror:8 row_mask:0xf bank_mask:0xf bound_ctrl:1
	v_mov_b32_dpp v90, v84 row_ror:8 row_mask:0xf bank_mask:0xf bound_ctrl:1
	v_cndmask_b32_e64 v84, v80, v92, s[0:1]
	v_cndmask_b32_e64 v80, v85, v80, s[0:1]
	v_cndmask_b32_e64 v85, v81, v93, s[0:1]
	v_cndmask_b32_e64 v81, v86, v81, s[0:1]
	v_cndmask_b32_e64 v86, v82, v88, s[0:1]
	v_cndmask_b32_e64 v82, v87, v82, s[0:1]
	v_cndmask_b32_e64 v87, v90, v89, s[0:1]
	v_cndmask_b32_e64 v83, v83, v90, s[0:1]
	v_or_b32_e32 v90, 32, v142
	v_or_b32_e32 v88, 40, v142
	s_and_b64 vcc, exec, s[6:7]
	s_mov_b64 s[28:29], -1
	s_cbranch_vccnz .LBB0_210
	v_and_b32_e32 v89, 0x1fe7, v90
	v_lshlrev_b32_e32 v92, s21, v89
	v_and_b32_e32 v92, 0x1ffe, v92
	v_lshrrev_b32_e32 v89, s17, v89
	v_lshlrev_b32_e32 v93, s21, v88
	v_and_b32_e32 v91, 0x1fef, v88
	v_and_b32_e32 v94, 0x1ffe, v93
	v_add_lshl_u32 v92, v92, v89, 7
	v_mov_b32_e32 v93, v133
	v_lshrrev_b32_e32 v91, s17, v91
	v_lshl_add_u64 v[92:93], v[144:145], 0, v[92:93]
	global_store_dwordx4 v[92:93], v[84:87], off sc1 nt
	v_add_lshl_u32 v92, v94, v91, 7
	v_mov_b32_e32 v93, v133
	v_lshl_add_u64 v[92:93], v[144:145], 0, v[92:93]
	global_store_dwordx4 v[92:93], v[80:83], off sc1 nt
	s_cbranch_execz .LBB0_211

; __device__ __forceinline__ unsigned pk2(float lo, float hi) { f32x2_t v = {lo, hi}; bf16x2_t b = __builtin_convertvector(v, bf16x2_t); return __builtin_bit_cast(unsigned, b); }
; __device__ __forceinline__ float silu_f(float v) { return v * __builtin_amdgcn_rcpf(1.f + __builtin_amdgcn_exp2f(-v * LOG2E)); }
; template <int CTRL> __device__ __forceinline__ unsigned dpp_mov(unsigned v) { return (unsigned)__builtin_amdgcn_update_dpp(0, (int)v, CTRL, 0xF, 0xF, true); }
;     __device__ __forceinline__ void operator()(const pg8::f32x4 (&acc)[2][2][4][2], const pg8::Unit& u, int wr, int wc, int fr, int fq) const {
;     ...
;                 pg8::f32x4 a0 = acc[ai][0][m][0], a1 = acc[ai][0][m][1], b0 = acc[ai][1][m][0], b1 = acc[ai][1][m][1];
;                 if (act) {
; #pragma unroll
;                     for (int e = 0; e < 4; ++e) { a0[e] = silu_f(a0[e]); a1[e] = silu_f(a1[e]); b0[e] = silu_f(b0[e]); b1[e] = silu_f(b1[e]); } }
;                 u32x4 A, B; A.x = pk2(a0[0], a0[1]); A.y = pk2(a0[2], a0[3]); A.z = pk2(a1[0], a1[1]); A.w = pk2(a1[2], a1[3]);
;                 B.x = pk2(b0[0], b0[1]); B.y = pk2(b0[2], b0[3]); B.z = pk2(b1[0], b1[1]); B.w = pk2(b1[2], b1[3]);
;                 u32x4 snd, rcv;
; #pragma unroll
;                 for (int e = 0; e < 4; ++e) { snd[e] = hi8 ? A[e] : B[e]; rcv[e] = dpp_mov<0x128>(snd[e]); }
;                 u32x4 d1, d2;
; #pragma unroll
;                 for (int e = 0; e < 4; ++e) { d1[e] = hi8 ? rcv[e] : A[e]; d2[e] = hi8 ? B[e] : rcv[e]; }
;                 const int row1 = rbase + ai * 128 + m * 16, row2 = row1 + 8;
;                 if (qkv) {
;                     const int bb = row1 >> 13, t1 = row1 & (SEQ - 1), t2 = row2 & (SEQ - 1);
;                     const int p1 = (t1 & dmask) * Lc + (t1 >> dsh), p2 = (t2 & dmask) * Lc + (t2 >> dsh);
;                     bf16_t* hb = base + (size_t)bb * 24 * SEQ * 64 + ecol;
;                     *(u32x4*)(hb + (size_t)p1 * 64) = d1; *(u32x4*)(hb + (size_t)p2 * 64) = d2;
.Lp1_nn3:
	v_cvt_pk_bf16_f32 v76, v76, v77
	v_cvt_pk_bf16_f32 v77, v78, v79
	v_cvt_pk_bf16_f32 v72, v72, v73
	v_cvt_pk_bf16_f32 v73, v74, v75
	v_cvt_pk_bf16_f32 v69, v68, v69
	v_cvt_pk_bf16_f32 v70, v70, v71
	v_cvt_pk_bf16_f32 v71, v64, v65
	v_cvt_pk_bf16_f32 v67, v66, v67
	v_cndmask_b32_e64 v64, v76, v69, s[0:1]
	v_cndmask_b32_e64 v65, v77, v70, s[0:1]
	v_cndmask_b32_e64 v66, v72, v71, s[0:1]
	v_cndmask_b32_e64 v68, v73, v67, s[0:1]
	v_mov_b32_dpp v64, v64 row_ror:8 row_mask:0xf bank_mask:0xf bound_ctrl:1
	v_mov_b32_dpp v65, v65 row_ror:8 row_mask:0xf bank_mask:0xf bound_ctrl:1
	v_mov_b32_dpp v66, v66 row_ror:8 row_mask:0xf bank_mask:0xf bound_ctrl:1
	v_mov_b32_dpp v74, v68 row_ror:8 row_mask:0xf bank_mask:0xf bound_ctrl:1
	v_cndmask_b32_e64 v68, v64, v76, s[0:1]
	v_cndmask_b32_e64 v64, v69, v64, s[0:1]
	v_cndmask_b32_e64 v69, v65, v77, s[0:1]
	v_cndmask_b32_e64 v65, v70, v65, s[0:1]
	v_cndmask_b32_e64 v70, v66, v72, s[0:1]
	v_cndmask_b32_e64 v66, v71, v66, s[0:1]
	v_cndmask_b32_e64 v71, v74, v73, s[0:1]
	v_cndmask_b32_e64 v67, v67, v74, s[0:1]
	v_or_b32_e32 v74, 48, v142
	v_or_b32_e32 v72, 56, v142
	s_and_b64 vcc, exec, s[6:7]
	s_mov_b64 s[28:29], -1
	s_cbranch_vccnz .LBB0_212
	v_and_b32_e32 v73, 0x1ff7, v74
	v_lshlrev_b32_e32 v76, s21, v73
	v_and_b32_e32 v76, 0x1ffe, v76
	v_lshrrev_b32_e32 v73, s17, v73
	v_lshlrev_b32_e32 v77, s21, v72
	v_and_b32_e32 v75, 0x1fff, v72
	v_and_b32_e32 v78, 0x1ffe, v77
	v_add_lshl_u32 v76, v76, v73, 7
	v_mov_b32_e32 v77, v133
	v_lshrrev_b32_e32 v75, s17, v75
	v_lshl_add_u64 v[76:77], v[144:145], 0, v[76:77]
	global_store_dwordx4 v[76:77], v[68:71], off sc1 nt
	v_add_lshl_u32 v76, v78, v75, 7
	v_mov_b32_e32 v77, v133
	v_lshl_add_u64 v[76:77], v[144:145], 0, v[76:77]
	global_store_dwordx4 v[76:77], v[64:67], off sc1 nt
	s_cbranch_execz .LBB0_213

; __device__ __forceinline__ unsigned pk2(float lo, float hi) { f32x2_t v = {lo, hi}; bf16x2_t b = __builtin_convertvector(v, bf16x2_t); return __builtin_bit_cast(unsigned, b); }
; __device__ __forceinline__ float silu_f(float v) { return v * __builtin_amdgcn_rcpf(1.f + __builtin_amdgcn_exp2f(-v * LOG2E)); }
; template <int CTRL> __device__ __forceinline__ unsigned dpp_mov(unsigned v) { return (unsigned)__builtin_amdgcn_update_dpp(0, (int)v, CTRL, 0xF, 0xF, true); }
;     __device__ __forceinline__ void operator()(const pg8::f32x4 (&acc)[2][2][4][2], const pg8::Unit& u, int wr, int wc, int fr, int fq) const {
;     ...
;                 pg8::f32x4 a0 = acc[ai][0][m][0], a1 = acc[ai][0][m][1], b0 = acc[ai][1][m][0], b1 = acc[ai][1][m][1];
;                 if (act) {
; #pragma unroll
;                     for (int e = 0; e < 4; ++e) { a0[e] = silu_f(a0[e]); a1[e] = silu_f(a1[e]); b0[e] = silu_f(b0[e]); b1[e] = silu_f(b1[e]); } }
;                 u32x4 A, B; A.x = pk2(a0[0], a0[1]); A.y = pk2(a0[2], a0[3]); A.z = pk2(a1[0], a1[1]); A.w = pk2(a1[2], a1[3]);
;                 B.x = pk2(b0[0], b0[1]); B.y = pk2(b0[2], b0[3]); B.z = pk2(b1[0], b1[1]); B.w = pk2(b1[2], b1[3]);
;                 u32x4 snd, rcv;
; #pragma unroll
;                 for (int e = 0; e < 4; ++e) { snd[e] = hi8 ? A[e] : B[e]; rcv[e] = dpp_mov<0x128>(snd[e]); }
;                 u32x4 d1, d2;
; #pragma unroll
;                 for (int e = 0; e < 4; ++e) { d1[e] = hi8 ? rcv[e] : A[e]; d2[e] = hi8 ? B[e] : rcv[e]; }
;                 const int row1 = rbase + ai * 128 + m * 16, row2 = row1 + 8;
;                 if (qkv) {
;                     const int bb = row1 >> 13, t1 = row1 & (SEQ - 1), t2 = row2 & (SEQ - 1);
;                     const int p1 = (t1 & dmask) * Lc + (t1 >> dsh), p2 = (t2 & dmask) * Lc + (t2 >> dsh);
;                     bf16_t* hb = base + (size_t)bb * 24 * SEQ * 64 + ecol;
;                     *(u32x4*)(hb + (size_t)p1 * 64) = d1; *(u32x4*)(hb + (size_t)p2 * 64) = d2;
.Lp1_nn4:
	v_add_u32_e32 v66, 0x80, v142
	v_ashrrev_i32_e32 v64, 13, v66
	v_mul_i32_i24_e32 v64, 24, v64
	v_cvt_pk_bf16_f32 v60, v60, v61
	v_cvt_pk_bf16_f32 v61, v62, v63
	v_cvt_pk_bf16_f32 v56, v56, v57
	v_cvt_pk_bf16_f32 v57, v58, v59
	v_cvt_pk_bf16_f32 v53, v52, v53
	v_cvt_pk_bf16_f32 v54, v54, v55
	v_cvt_pk_bf16_f32 v55, v48, v49
	v_cvt_pk_bf16_f32 v51, v50, v51
	v_ashrrev_i32_e32 v65, 31, v64
	v_cndmask_b32_e64 v48, v60, v53, s[0:1]
	v_cndmask_b32_e64 v49, v61, v54, s[0:1]
	v_cndmask_b32_e64 v50, v56, v55, s[0:1]
	v_cndmask_b32_e64 v52, v57, v51, s[0:1]
	v_lshlrev_b64 v[64:65], 20, v[64:65]
	v_mov_b32_dpp v48, v48 row_ror:8 row_mask:0xf bank_mask:0xf bound_ctrl:1
	v_mov_b32_dpp v49, v49 row_ror:8 row_mask:0xf bank_mask:0xf bound_ctrl:1
	v_mov_b32_dpp v50, v50 row_ror:8 row_mask:0xf bank_mask:0xf bound_ctrl:1
	v_mov_b32_dpp v58, v52 row_ror:8 row_mask:0xf bank_mask:0xf bound_ctrl:1
	v_lshl_add_u64 v[64:65], v[140:141], 0, v[64:65]
	v_cndmask_b32_e64 v52, v48, v60, s[0:1]
	v_cndmask_b32_e64 v48, v53, v48, s[0:1]
	v_cndmask_b32_e64 v53, v49, v61, s[0:1]
	v_cndmask_b32_e64 v49, v54, v49, s[0:1]
	v_cndmask_b32_e64 v54, v50, v56, s[0:1]
	v_cndmask_b32_e64 v50, v55, v50, s[0:1]
	v_cndmask_b32_e64 v55, v58, v57, s[0:1]
	v_cndmask_b32_e64 v51, v51, v58, s[0:1]
	v_add_u32_e32 v56, 0x88, v142
	s_and_b64 vcc, exec, s[6:7]
	s_mov_b64 s[28:29], -1
	s_cbranch_vccnz .LBB0_214
	v_and_b32_e32 v57, 0x1fc7, v66
	v_lshlrev_b32_e32 v59, s21, v57
	v_and_b32_e32 v58, 0x1fcf, v56
	v_and_b32_e32 v59, 0x1ffe, v59
	v_lshrrev_b32_e32 v57, s17, v57
	v_lshlrev_b32_e32 v60, s21, v56
	v_lshrrev_b32_e32 v61, s17, v58
	v_add_lshl_u32 v58, v59, v57, 7
	v_mov_b32_e32 v59, v133
	v_and_b32_e32 v60, 0x1ffe, v60
	v_lshl_add_u64 v[58:59], v[64:65], 0, v[58:59]
	global_store_dwordx4 v[58:59], v[52:55], off sc1 nt
	v_add_lshl_u32 v58, v60, v61, 7
	v_mov_b32_e32 v59, v133
	v_lshl_add_u64 v[58:59], v[64:65], 0, v[58:59]
	global_store_dwordx4 v[58:59], v[48:51], off sc1 nt
	s_cbranch_execz .LBB0_215

; __device__ __forceinline__ unsigned pk2(float lo, float hi) { f32x2_t v = {lo, hi}; bf16x2_t b = __builtin_convertvector(v, bf16x2_t); return __builtin_bit_cast(unsigned, b); }
; __device__ __forceinline__ float silu_f(float v) { return v * __builtin_amdgcn_rcpf(1.f + __builtin_amdgcn_exp2f(-v * LOG2E)); }
; template <int CTRL> __device__ __forceinline__ unsigned dpp_mov(unsigned v) { return (unsigned)__builtin_amdgcn_update_dpp(0, (int)v, CTRL, 0xF, 0xF, true); }
;     __device__ __forceinline__ void operator()(const pg8::f32x4 (&acc)[2][2][4][2], const pg8::Unit& u, int wr, int wc, int fr, int fq) const {
;     ...
;                 pg8::f32x4 a0 = acc[ai][0][m][0], a1 = acc[ai][0][m][1], b0 = acc[ai][1][m][0], b1 = acc[ai][1][m][1];
;                 if (act) {
; #pragma unroll
;                     for (int e = 0; e < 4; ++e) { a0[e] = silu_f(a0[e]); a1[e] = silu_f(a1[e]); b0[e] = silu_f(b0[e]); b1[e] = silu_f(b1[e]); } }
;                 u32x4 A, B; A.x = pk2(a0[0], a0[1]); A.y = pk2(a0[2], a0[3]); A.z = pk2(a1[0], a1[1]); A.w = pk2(a1[2], a1[3]);
;                 B.x = pk2(b0[0], b0[1]); B.y = pk2(b0[2], b0[3]); B.z = pk2(b1[0], b1[1]); B.w = pk2(b1[2], b1[3]);
;                 u32x4 snd, rcv;
; #pragma unroll
;                 for (int e = 0; e < 4; ++e) { snd[e] = hi8 ? A[e] : B[e]; rcv[e] = dpp_mov<0x128>(snd[e]); }
;                 u32x4 d1, d2;
; #pragma unroll
;                 for (int e = 0; e < 4; ++e) { d1[e] = hi8 ? rcv[e] : A[e]; d2[e] = hi8 ? B[e] : rcv[e]; }
;                 const int row1 = rbase + ai * 128 + m * 16, row2 = row1 + 8;
;                 if (qkv) {
;                     const int bb = row1 >> 13, t1 = row1 & (SEQ - 1), t2 = row2 & (SEQ - 1);
;                     const int p1 = (t1 & dmask) * Lc + (t1 >> dsh), p2 = (t2 & dmask) * Lc + (t2 >> dsh);
;                     bf16_t* hb = base + (size_t)bb * 24 * SEQ * 64 + ecol;
;                     *(u32x4*)(hb + (size_t)p1 * 64) = d1; *(u32x4*)(hb + (size_t)p2 * 64) = d2;
.Lp1_nn5:
	v_cvt_pk_bf16_f32 v44, v44, v45
	v_cvt_pk_bf16_f32 v45, v46, v47
	v_cvt_pk_bf16_f32 v40, v40, v41
	v_cvt_pk_bf16_f32 v41, v42, v43
	v_cvt_pk_bf16_f32 v37, v36, v37
	v_cvt_pk_bf16_f32 v38, v38, v39
	v_cvt_pk_bf16_f32 v39, v32, v33
	v_cvt_pk_bf16_f32 v35, v34, v35
	v_cndmask_b32_e64 v32, v44, v37, s[0:1]
	v_cndmask_b32_e64 v33, v45, v38, s[0:1]
	v_cndmask_b32_e64 v34, v40, v39, s[0:1]
	v_cndmask_b32_e64 v36, v41, v35, s[0:1]
	v_mov_b32_dpp v32, v32 row_ror:8 row_mask:0xf bank_mask:0xf bound_ctrl:1
	v_mov_b32_dpp v33, v33 row_ror:8 row_mask:0xf bank_mask:0xf bound_ctrl:1
	v_mov_b32_dpp v34, v34 row_ror:8 row_mask:0xf bank_mask:0xf bound_ctrl:1
	v_mov_b32_dpp v42, v36 row_ror:8 row_mask:0xf bank_mask:0xf bound_ctrl:1
	v_cndmask_b32_e64 v36, v32, v44, s[0:1]
	v_cndmask_b32_e64 v32, v37, v32, s[0:1]
	v_cndmask_b32_e64 v37, v33, v45, s[0:1]
	v_cndmask_b32_e64 v33, v38, v33, s[0:1]
	v_cndmask_b32_e64 v38, v34, v40, s[0:1]
	v_cndmask_b32_e64 v34, v39, v34, s[0:1]
	v_cndmask_b32_e64 v39, v42, v41, s[0:1]
	v_cndmask_b32_e64 v35, v35, v42, s[0:1]
	v_add_u32_e32 v42, 0x90, v142
	v_add_u32_e32 v40, 0x98, v142
	s_and_b64 vcc, exec, s[6:7]
	s_mov_b64 s[28:29], -1
	s_cbranch_vccnz .LBB0_216
	v_and_b32_e32 v41, 0x1fd7, v42
	v_lshlrev_b32_e32 v44, s21, v41
	v_and_b32_e32 v44, 0x1ffe, v44
	v_lshrrev_b32_e32 v41, s17, v41
	v_lshlrev_b32_e32 v45, s21, v40
	v_and_b32_e32 v43, 0x1fdf, v40
	v_and_b32_e32 v46, 0x1ffe, v45
	v_add_lshl_u32 v44, v44, v41, 7
	v_mov_b32_e32 v45, v133
	v_lshrrev_b32_e32 v43, s17, v43
	v_lshl_add_u64 v[44:45], v[64:65], 0, v[44:45]
	global_store_dwordx4 v[44:45], v[36:39], off sc1 nt
	v_add_lshl_u32 v44, v46, v43, 7
	v_mov_b32_e32 v45, v133
	v_lshl_add_u64 v[44:45], v[64:65], 0, v[44:45]
	global_store_dwordx4 v[44:45], v[32:35], off sc1 nt
	s_cbranch_execz .LBB0_217

; __device__ __forceinline__ unsigned pk2(float lo, float hi) { f32x2_t v = {lo, hi}; bf16x2_t b = __builtin_convertvector(v, bf16x2_t); return __builtin_bit_cast(unsigned, b); }
; __device__ __forceinline__ float silu_f(float v) { return v * __builtin_amdgcn_rcpf(1.f + __builtin_amdgcn_exp2f(-v * LOG2E)); }
; template <int CTRL> __device__ __forceinline__ unsigned dpp_mov(unsigned v) { return (unsigned)__builtin_amdgcn_update_dpp(0, (int)v, CTRL, 0xF, 0xF, true); }
;     __device__ __forceinline__ void operator()(const pg8::f32x4 (&acc)[2][2][4][2], const pg8::Unit& u, int wr, int wc, int fr, int fq) const {
;     ...
;                 pg8::f32x4 a0 = acc[ai][0][m][0], a1 = acc[ai][0][m][1], b0 = acc[ai][1][m][0], b1 = acc[ai][1][m][1];
;                 if (act) {
; #pragma unroll
;                     for (int e = 0; e < 4; ++e) { a0[e] = silu_f(a0[e]); a1[e] = silu_f(a1[e]); b0[e] = silu_f(b0[e]); b1[e] = silu_f(b1[e]); } }
;                 u32x4 A, B; A.x = pk2(a0[0], a0[1]); A.y = pk2(a0[2], a0[3]); A.z = pk2(a1[0], a1[1]); A.w = pk2(a1[2], a1[3]);
;                 B.x = pk2(b0[0], b0[1]); B.y = pk2(b0[2], b0[3]); B.z = pk2(b1[0], b1[1]); B.w = pk2(b1[2], b1[3]);
;                 u32x4 snd, rcv;
; #pragma unroll
;                 for (int e = 0; e < 4; ++e) { snd[e] = hi8 ? A[e] : B[e]; rcv[e] = dpp_mov<0x128>(snd[e]); }
;                 u32x4 d1, d2;
; #pragma unroll
;                 for (int e = 0; e < 4; ++e) { d1[e] = hi8 ? rcv[e] : A[e]; d2[e] = hi8 ? B[e] : rcv[e]; }
;                 const int row1 = rbase + ai * 128 + m * 16, row2 = row1 + 8;
;                 if (qkv) {
;                     const int bb = row1 >> 13, t1 = row1 & (SEQ - 1), t2 = row2 & (SEQ - 1);
;                     const int p1 = (t1 & dmask) * Lc + (t1 >> dsh), p2 = (t2 & dmask) * Lc + (t2 >> dsh);
;                     bf16_t* hb = base + (size_t)bb * 24 * SEQ * 64 + ecol;
;                     *(u32x4*)(hb + (size_t)p1 * 64) = d1; *(u32x4*)(hb + (size_t)p2 * 64) = d2;
.Lp1_nn6:
	v_cvt_pk_bf16_f32 v28, v28, v29
	v_cvt_pk_bf16_f32 v29, v30, v31
	v_cvt_pk_bf16_f32 v24, v24, v25
	v_cvt_pk_bf16_f32 v25, v26, v27
	v_cvt_pk_bf16_f32 v21, v20, v21
	v_cvt_pk_bf16_f32 v22, v22, v23
	v_cvt_pk_bf16_f32 v23, v16, v17
	v_cvt_pk_bf16_f32 v19, v18, v19
	v_cndmask_b32_e64 v16, v28, v21, s[0:1]
	v_cndmask_b32_e64 v17, v29, v22, s[0:1]
	v_cndmask_b32_e64 v18, v24, v23, s[0:1]
	v_cndmask_b32_e64 v20, v25, v19, s[0:1]
	v_mov_b32_dpp v16, v16 row_ror:8 row_mask:0xf bank_mask:0xf bound_ctrl:1
	v_mov_b32_dpp v17, v17 row_ror:8 row_mask:0xf bank_mask:0xf bound_ctrl:1
	v_mov_b32_dpp v18, v18 row_ror:8 row_mask:0xf bank_mask:0xf bound_ctrl:1
	v_mov_b32_dpp v26, v20 row_ror:8 row_mask:0xf bank_mask:0xf bound_ctrl:1
	v_cndmask_b32_e64 v20, v16, v28, s[0:1]
	v_cndmask_b32_e64 v16, v21, v16, s[0:1]
	v_cndmask_b32_e64 v21, v17, v29, s[0:1]
	v_cndmask_b32_e64 v17, v22, v17, s[0:1]
	v_cndmask_b32_e64 v22, v18, v24, s[0:1]
	v_cndmask_b32_e64 v18, v23, v18, s[0:1]
	v_cndmask_b32_e64 v23, v26, v25, s[0:1]
	v_cndmask_b32_e64 v19, v19, v26, s[0:1]
	v_add_u32_e32 v26, 0xa0, v142
	v_add_u32_e32 v24, 0xa8, v142
	s_and_b64 vcc, exec, s[6:7]
	s_mov_b64 s[28:29], -1
	s_cbranch_vccnz .LBB0_218
	v_and_b32_e32 v25, 0x1fe7, v26
	v_lshlrev_b32_e32 v28, s21, v25
	v_and_b32_e32 v28, 0x1ffe, v28
	v_lshrrev_b32_e32 v25, s17, v25
	v_lshlrev_b32_e32 v29, s21, v24
	v_and_b32_e32 v27, 0x1fef, v24
	v_and_b32_e32 v30, 0x1ffe, v29
	v_add_lshl_u32 v28, v28, v25, 7
	v_mov_b32_e32 v29, v133
	v_lshrrev_b32_e32 v27, s17, v27
	v_lshl_add_u64 v[28:29], v[64:65], 0, v[28:29]
	global_store_dwordx4 v[28:29], v[20:23], off sc1 nt
	v_add_lshl_u32 v28, v30, v27, 7
	v_mov_b32_e32 v29, v133
	v_lshl_add_u64 v[28:29], v[64:65], 0, v[28:29]
	global_store_dwordx4 v[28:29], v[16:19], off sc1 nt
	s_cbranch_execz .LBB0_219

; __device__ __forceinline__ unsigned pk2(float lo, float hi) { f32x2_t v = {lo, hi}; bf16x2_t b = __builtin_convertvector(v, bf16x2_t); return __builtin_bit_cast(unsigned, b); }
; __device__ __forceinline__ float silu_f(float v) { return v * __builtin_amdgcn_rcpf(1.f + __builtin_amdgcn_exp2f(-v * LOG2E)); }
; template <int CTRL> __device__ __forceinline__ unsigned dpp_mov(unsigned v) { return (unsigned)__builtin_amdgcn_update_dpp(0, (int)v, CTRL, 0xF, 0xF, true); }
;     __device__ __forceinline__ void operator()(const pg8::f32x4 (&acc)[2][2][4][2], const pg8::Unit& u, int wr, int wc, int fr, int fq) const {
;     ...
;                 pg8::f32x4 a0 = acc[ai][0][m][0], a1 = acc[ai][0][m][1], b0 = acc[ai][1][m][0], b1 = acc[ai][1][m][1];
;                 if (act) {
; #pragma unroll
;                     for (int e = 0; e < 4; ++e) { a0[e] = silu_f(a0[e]); a1[e] = silu_f(a1[e]); b0[e] = silu_f(b0[e]); b1[e] = silu_f(b1[e]); } }
;                 u32x4 A, B; A.x = pk2(a0[0], a0[1]); A.y = pk2(a0[2], a0[3]); A.z = pk2(a1[0], a1[1]); A.w = pk2(a1[2], a1[3]);
;                 B.x = pk2(b0[0], b0[1]); B.y = pk2(b0[2], b0[3]); B.z = pk2(b1[0], b1[1]); B.w = pk2(b1[2], b1[3]);
;                 u32x4 snd, rcv;
; #pragma unroll
;                 for (int e = 0; e < 4; ++e) { snd[e] = hi8 ? A[e] : B[e]; rcv[e] = dpp_mov<0x128>(snd[e]); }
;                 u32x4 d1, d2;
; #pragma unroll
;                 for (int e = 0; e < 4; ++e) { d1[e] = hi8 ? rcv[e] : A[e]; d2[e] = hi8 ? B[e] : rcv[e]; }
;                 const int row1 = rbase + ai * 128 + m * 16, row2 = row1 + 8;
;                 if (qkv) {
;                     const int bb = row1 >> 13, t1 = row1 & (SEQ - 1), t2 = row2 & (SEQ - 1);
;                     const int p1 = (t1 & dmask) * Lc + (t1 >> dsh), p2 = (t2 & dmask) * Lc + (t2 >> dsh);
;                     bf16_t* hb = base + (size_t)bb * 24 * SEQ * 64 + ecol;
;                     *(u32x4*)(hb + (size_t)p1 * 64) = d1; *(u32x4*)(hb + (size_t)p2 * 64) = d2;
.Lp1_nn7:
	v_cvt_pk_bf16_f32 v12, v12, v13
	v_cvt_pk_bf16_f32 v13, v14, v15
	v_cvt_pk_bf16_f32 v8, v8, v9
	v_cvt_pk_bf16_f32 v9, v10, v11
	v_cvt_pk_bf16_f32 v5, v4, v5
	v_cvt_pk_bf16_f32 v6, v6, v7
	v_cvt_pk_bf16_f32 v7, v0, v1
	v_cvt_pk_bf16_f32 v3, v2, v3
	v_cndmask_b32_e64 v0, v12, v5, s[0:1]
	v_cndmask_b32_e64 v1, v13, v6, s[0:1]
	v_cndmask_b32_e64 v2, v8, v7, s[0:1]
	v_cndmask_b32_e64 v4, v9, v3, s[0:1]
	v_mov_b32_dpp v0, v0 row_ror:8 row_mask:0xf bank_mask:0xf bound_ctrl:1
	v_mov_b32_dpp v1, v1 row_ror:8 row_mask:0xf bank_mask:0xf bound_ctrl:1
	v_mov_b32_dpp v2, v2 row_ror:8 row_mask:0xf bank_mask:0xf bound_ctrl:1
	v_mov_b32_dpp v10, v4 row_ror:8 row_mask:0xf bank_mask:0xf bound_ctrl:1
	v_cndmask_b32_e64 v4, v0, v12, s[0:1]
	v_cndmask_b32_e64 v0, v5, v0, s[0:1]
	v_cndmask_b32_e64 v5, v1, v13, s[0:1]
	v_cndmask_b32_e64 v1, v6, v1, s[0:1]
	v_cndmask_b32_e64 v6, v2, v8, s[0:1]
	v_cndmask_b32_e64 v2, v7, v2, s[0:1]
	v_cndmask_b32_e64 v7, v10, v9, s[0:1]
	v_cndmask_b32_e64 v3, v3, v10, s[0:1]
	v_add_u32_e32 v10, 0xb0, v142
	v_add_u32_e32 v8, 0xb8, v142
	s_and_b64 vcc, exec, s[6:7]
	s_mov_b64 s[4:5], -1
	s_cbranch_vccnz .LBB0_220
	v_and_b32_e32 v9, 0x1ff7, v10
	v_lshlrev_b32_e32 v12, s21, v9
	v_and_b32_e32 v12, 0x1ffe, v12
	v_lshrrev_b32_e32 v9, s17, v9
	v_lshlrev_b32_e32 v13, s21, v8
	v_and_b32_e32 v11, 0x1fff, v8
	v_and_b32_e32 v14, 0x1ffe, v13
	v_add_lshl_u32 v12, v12, v9, 7
	v_mov_b32_e32 v13, v133
	v_lshrrev_b32_e32 v11, s17, v11
	v_lshl_add_u64 v[12:13], v[64:65], 0, v[12:13]
	global_store_dwordx4 v[12:13], v[4:7], off sc1 nt
	v_add_lshl_u32 v12, v14, v11, 7
	v_mov_b32_e32 v13, v133
	v_lshl_add_u64 v[12:13], v[64:65], 0, v[12:13]
	global_store_dwordx4 v[12:13], v[0:3], off sc1 nt
	s_cbranch_execz .LBB0_221

;     __device__ __forceinline__ void operator()(const pg8::f32x4 (&acc)[2][2][4][2], const pg8::Unit& u, int wr, int wc, int fr, int fq) const {
;     ...
;                 const int row1 = rbase + ai * 128 + m * 16, row2 = row1 + 8;
;                 if (qkv) {
;                     const int bb = row1 >> 13, t1 = row1 & (SEQ - 1), t2 = row2 & (SEQ - 1);
;                     const int p1 = (t1 & dmask) * Lc + (t1 >> dsh), p2 = (t2 & dmask) * Lc + (t2 >> dsh);
;                     bf16_t* hb = base + (size_t)bb * 24 * SEQ * 64 + ecol;
;                     *(u32x4*)(hb + (size_t)p1 * 64) = d1; *(u32x4*)(hb + (size_t)p2 * 64) = d2;
;                 } else {
;                     *(u32x4*)(base + (size_t)row1 * ld + ecol) = d1; *(u32x4*)(base + (size_t)row2 * ld + ecol) = d2;
.LBB0_207:
	v_ashrrev_i32_e32 v143, 31, v142
	v_lshlrev_b64 v[122:123], s8, v[142:143]
	v_lshl_add_u64 v[122:123], v[122:123], 1, v[140:141]
	v_ashrrev_i32_e32 v121, 31, v120
	global_store_dwordx4 v[122:123], v[116:119], off sc1 nt
	s_nop 1
	v_lshlrev_b64 v[116:117], s8, v[120:121]
	v_lshl_add_u64 v[116:117], v[116:117], 1, v[140:141]
	global_store_dwordx4 v[116:117], v[112:115], off sc1 nt
	s_and_b64 vcc, exec, s[4:5]
	s_cbranch_vccz .LBB0_178
	s_branch .LBB0_179

;     __device__ __forceinline__ void operator()(const pg8::f32x4 (&acc)[2][2][4][2], const pg8::Unit& u, int wr, int wc, int fr, int fq) const {
;     ...
;                 const int row1 = rbase + ai * 128 + m * 16, row2 = row1 + 8;
;                 if (qkv) {
;                     const int bb = row1 >> 13, t1 = row1 & (SEQ - 1), t2 = row2 & (SEQ - 1);
;                     const int p1 = (t1 & dmask) * Lc + (t1 >> dsh), p2 = (t2 & dmask) * Lc + (t2 >> dsh);
;                     bf16_t* hb = base + (size_t)bb * 24 * SEQ * 64 + ecol;
;                     *(u32x4*)(hb + (size_t)p1 * 64) = d1; *(u32x4*)(hb + (size_t)p2 * 64) = d2;
;                 } else {
;                     *(u32x4*)(base + (size_t)row1 * ld + ecol) = d1; *(u32x4*)(base + (size_t)row2 * ld + ecol) = d2;
.LBB0_209:
	v_ashrrev_i32_e32 v107, 31, v106
	v_lshlrev_b64 v[106:107], s8, v[106:107]
	v_lshl_add_u64 v[106:107], v[106:107], 1, v[140:141]
	v_ashrrev_i32_e32 v105, 31, v104
	global_store_dwordx4 v[106:107], v[100:103], off sc1 nt
	s_nop 1
	v_lshlrev_b64 v[100:101], s8, v[104:105]
	v_lshl_add_u64 v[100:101], v[100:101], 1, v[140:141]
	global_store_dwordx4 v[100:101], v[96:99], off sc1 nt
	s_and_b64 vcc, exec, s[4:5]
	s_cbranch_vccz .LBB0_182
	s_branch .LBB0_183

;     __device__ __forceinline__ void operator()(const pg8::f32x4 (&acc)[2][2][4][2], const pg8::Unit& u, int wr, int wc, int fr, int fq) const {
;     ...
;                 const int row1 = rbase + ai * 128 + m * 16, row2 = row1 + 8;
;                 if (qkv) {
;                     const int bb = row1 >> 13, t1 = row1 & (SEQ - 1), t2 = row2 & (SEQ - 1);
;                     const int p1 = (t1 & dmask) * Lc + (t1 >> dsh), p2 = (t2 & dmask) * Lc + (t2 >> dsh);
;                     bf16_t* hb = base + (size_t)bb * 24 * SEQ * 64 + ecol;
;                     *(u32x4*)(hb + (size_t)p1 * 64) = d1; *(u32x4*)(hb + (size_t)p2 * 64) = d2;
;                 } else {
;                     *(u32x4*)(base + (size_t)row1 * ld + ecol) = d1; *(u32x4*)(base + (size_t)row2 * ld + ecol) = d2;
.LBB0_211:
	v_ashrrev_i32_e32 v91, 31, v90
	v_lshlrev_b64 v[90:91], s8, v[90:91]
	v_lshl_add_u64 v[90:91], v[90:91], 1, v[140:141]
	v_ashrrev_i32_e32 v89, 31, v88
	global_store_dwordx4 v[90:91], v[84:87], off sc1 nt
	s_nop 1
	v_lshlrev_b64 v[84:85], s8, v[88:89]
	v_lshl_add_u64 v[84:85], v[84:85], 1, v[140:141]
	global_store_dwordx4 v[84:85], v[80:83], off sc1 nt
	s_and_b64 vcc, exec, s[4:5]
	s_cbranch_vccz .LBB0_186
	s_branch .LBB0_187

;     __device__ __forceinline__ void operator()(const pg8::f32x4 (&acc)[2][2][4][2], const pg8::Unit& u, int wr, int wc, int fr, int fq) const {
;     ...
;                 const int row1 = rbase + ai * 128 + m * 16, row2 = row1 + 8;
;                 if (qkv) {
;                     const int bb = row1 >> 13, t1 = row1 & (SEQ - 1), t2 = row2 & (SEQ - 1);
;                     const int p1 = (t1 & dmask) * Lc + (t1 >> dsh), p2 = (t2 & dmask) * Lc + (t2 >> dsh);
;                     bf16_t* hb = base + (size_t)bb * 24 * SEQ * 64 + ecol;
;                     *(u32x4*)(hb + (size_t)p1 * 64) = d1; *(u32x4*)(hb + (size_t)p2 * 64) = d2;
;                 } else {
;                     *(u32x4*)(base + (size_t)row1 * ld + ecol) = d1; *(u32x4*)(base + (size_t)row2 * ld + ecol) = d2;
.LBB0_213:
	v_ashrrev_i32_e32 v75, 31, v74
	v_lshlrev_b64 v[74:75], s8, v[74:75]
	v_lshl_add_u64 v[74:75], v[74:75], 1, v[140:141]
	v_ashrrev_i32_e32 v73, 31, v72
	global_store_dwordx4 v[74:75], v[68:71], off sc1 nt
	s_nop 1
	v_lshlrev_b64 v[68:69], s8, v[72:73]
	v_lshl_add_u64 v[68:69], v[68:69], 1, v[140:141]
	global_store_dwordx4 v[68:69], v[64:67], off sc1 nt
	s_and_b64 vcc, exec, s[4:5]
	s_cbranch_vccz .LBB0_190
	s_branch .LBB0_191

;     __device__ __forceinline__ void operator()(const pg8::f32x4 (&acc)[2][2][4][2], const pg8::Unit& u, int wr, int wc, int fr, int fq) const {
;     ...
;                 const int row1 = rbase + ai * 128 + m * 16, row2 = row1 + 8;
;                 if (qkv) {
;                     const int bb = row1 >> 13, t1 = row1 & (SEQ - 1), t2 = row2 & (SEQ - 1);
;                     const int p1 = (t1 & dmask) * Lc + (t1 >> dsh), p2 = (t2 & dmask) * Lc + (t2 >> dsh);
;                     bf16_t* hb = base + (size_t)bb * 24 * SEQ * 64 + ecol;
;                     *(u32x4*)(hb + (size_t)p1 * 64) = d1; *(u32x4*)(hb + (size_t)p2 * 64) = d2;
;                 } else {
;                     *(u32x4*)(base + (size_t)row1 * ld + ecol) = d1; *(u32x4*)(base + (size_t)row2 * ld + ecol) = d2;
.LBB0_215:
	v_ashrrev_i32_e32 v67, 31, v66
	v_lshlrev_b64 v[58:59], s8, v[66:67]
	v_lshl_add_u64 v[58:59], v[58:59], 1, v[140:141]
	v_ashrrev_i32_e32 v57, 31, v56
	global_store_dwordx4 v[58:59], v[52:55], off sc1 nt
	s_nop 1
	v_lshlrev_b64 v[52:53], s8, v[56:57]
	v_lshl_add_u64 v[52:53], v[52:53], 1, v[140:141]
	global_store_dwordx4 v[52:53], v[48:51], off sc1 nt
	s_and_b64 vcc, exec, s[4:5]
	s_cbranch_vccz .LBB0_194
	s_branch .LBB0_195

;     __device__ __forceinline__ void operator()(const pg8::f32x4 (&acc)[2][2][4][2], const pg8::Unit& u, int wr, int wc, int fr, int fq) const {
;     ...
;                 const int row1 = rbase + ai * 128 + m * 16, row2 = row1 + 8;
;                 if (qkv) {
;                     const int bb = row1 >> 13, t1 = row1 & (SEQ - 1), t2 = row2 & (SEQ - 1);
;                     const int p1 = (t1 & dmask) * Lc + (t1 >> dsh), p2 = (t2 & dmask) * Lc + (t2 >> dsh);
;                     bf16_t* hb = base + (size_t)bb * 24 * SEQ * 64 + ecol;
;                     *(u32x4*)(hb + (size_t)p1 * 64) = d1; *(u32x4*)(hb + (size_t)p2 * 64) = d2;
;                 } else {
;                     *(u32x4*)(base + (size_t)row1 * ld + ecol) = d1; *(u32x4*)(base + (size_t)row2 * ld + ecol) = d2;
.LBB0_217:
	v_ashrrev_i32_e32 v43, 31, v42
	v_lshlrev_b64 v[42:43], s8, v[42:43]
	v_lshl_add_u64 v[42:43], v[42:43], 1, v[140:141]
	v_ashrrev_i32_e32 v41, 31, v40
	global_store_dwordx4 v[42:43], v[36:39], off sc1 nt
	s_nop 1
	v_lshlrev_b64 v[36:37], s8, v[40:41]
	v_lshl_add_u64 v[36:37], v[36:37], 1, v[140:141]
	global_store_dwordx4 v[36:37], v[32:35], off sc1 nt
	s_and_b64 vcc, exec, s[4:5]
	s_cbranch_vccz .LBB0_198
	s_branch .LBB0_199

;     __device__ __forceinline__ void operator()(const pg8::f32x4 (&acc)[2][2][4][2], const pg8::Unit& u, int wr, int wc, int fr, int fq) const {
;     ...
;                 const int row1 = rbase + ai * 128 + m * 16, row2 = row1 + 8;
;                 if (qkv) {
;                     const int bb = row1 >> 13, t1 = row1 & (SEQ - 1), t2 = row2 & (SEQ - 1);
;                     const int p1 = (t1 & dmask) * Lc + (t1 >> dsh), p2 = (t2 & dmask) * Lc + (t2 >> dsh);
;                     bf16_t* hb = base + (size_t)bb * 24 * SEQ * 64 + ecol;
;                     *(u32x4*)(hb + (size_t)p1 * 64) = d1; *(u32x4*)(hb + (size_t)p2 * 64) = d2;
;                 } else {
;                     *(u32x4*)(base + (size_t)row1 * ld + ecol) = d1; *(u32x4*)(base + (size_t)row2 * ld + ecol) = d2;
.LBB0_219:
	v_ashrrev_i32_e32 v27, 31, v26
	v_lshlrev_b64 v[26:27], s8, v[26:27]
	v_lshl_add_u64 v[26:27], v[26:27], 1, v[140:141]
	v_ashrrev_i32_e32 v25, 31, v24
	global_store_dwordx4 v[26:27], v[20:23], off sc1 nt
	s_nop 1
	v_lshlrev_b64 v[20:21], s8, v[24:25]
	v_lshl_add_u64 v[20:21], v[20:21], 1, v[140:141]
	global_store_dwordx4 v[20:21], v[16:19], off sc1 nt
	s_and_b64 vcc, exec, s[4:5]
	s_cbranch_vccz .LBB0_202
	s_branch .LBB0_203

;     __device__ __forceinline__ void operator()(const pg8::f32x4 (&acc)[2][2][4][2], const pg8::Unit& u, int wr, int wc, int fr, int fq) const {
;     ...
;                 const int row1 = rbase + ai * 128 + m * 16, row2 = row1 + 8;
;                 if (qkv) {
;                     const int bb = row1 >> 13, t1 = row1 & (SEQ - 1), t2 = row2 & (SEQ - 1);
;                     const int p1 = (t1 & dmask) * Lc + (t1 >> dsh), p2 = (t2 & dmask) * Lc + (t2 >> dsh);
;                     bf16_t* hb = base + (size_t)bb * 24 * SEQ * 64 + ecol;
;                     *(u32x4*)(hb + (size_t)p1 * 64) = d1; *(u32x4*)(hb + (size_t)p2 * 64) = d2;
;                 } else {
;                     *(u32x4*)(base + (size_t)row1 * ld + ecol) = d1; *(u32x4*)(base + (size_t)row2 * ld + ecol) = d2;
.LBB0_221:
	v_ashrrev_i32_e32 v11, 31, v10
	v_lshlrev_b64 v[10:11], s8, v[10:11]
	v_lshl_add_u64 v[10:11], v[10:11], 1, v[140:141]
	v_ashrrev_i32_e32 v9, 31, v8
	global_store_dwordx4 v[10:11], v[4:7], off sc1 nt
	s_nop 1
	v_lshlrev_b64 v[4:5], s8, v[8:9]
	v_lshl_add_u64 v[4:5], v[4:5], 1, v[140:141]
	global_store_dwordx4 v[4:5], v[0:3], off sc1 nt
	s_andn2_b64 vcc, exec, s[22:23]
	s_mov_b64 s[4:5], -1
	s_cbranch_vccnz .LBB0_153

;     __device__ __forceinline__ void operator()(const pg8::f32x4 (&acc)[2][2][4][2], const pg8::Unit& u, int wr, int wc, int fr, int fq) const {
;         const int row0 = u.pm * 256 + wr * 64 + fr, col0 = u.pn * 256 + wc * 32 + 4 * fq;
; #pragma unroll
;         for (int ai = 0; ai < 2; ++ai)
; #pragma unroll
;             for (int m = 0; m < 4; ++m) { const size_t off = (size_t)(row0 + ai * 128 + m * 16) * DM + col0;
; #pragma unroll
;                 for (int bj = 0; bj < 2; ++bj)
; #pragma unroll
;                     for (int n = 0; n < 2; ++n) { const size_t o2 = off + bj * 128 + n * 16; *(pg8::f32x4*)(out + o2) = *(const pg8::f32x4*)(x + o2) + acc[ai][bj][m][n]; }
;                 if (m & 1) asm volatile("" ::: "memory"); }
.LBB0_481:
	v_lshl_add_u32 v146, s26, 8, v136
	v_lshl_or_b32 v148, s55, 8, v138
	v_ashrrev_i32_e32 v147, 31, v146
	v_ashrrev_i32_e32 v149, 31, v148
	v_lshlrev_b64 v[134:135], 10, v[146:147]
	v_lshl_add_u64 v[134:135], v[134:135], 0, v[148:149]
	v_lshlrev_b64 v[134:135], 2, v[134:135]
	s_andn2_b64 vcc, exec, s[20:21]
	s_mov_b64 s[20:21], -1
	v_mbcnt_lo_u32_b32 v242, -1, 0
	v_mbcnt_hi_u32_b32 v242, -1, v242
	v_and_b32_e32 v242, 8, v242
	v_cmp_ne_u32_e64 s[94:95], 0, v242
	v_mul_u32_u24_e32 v242, 0xff8, v242
	v_sub_u32_e32 v134, v134, v242
	v_mov_b32_e32 v218, v134
	v_add_u32_e32 v219, 0x10000, v134
	v_add_u32_e32 v220, 0x20000, v134
	v_add_u32_e32 v221, 0x30000, v134
	v_add_u32_e32 v222, 0x80000, v134
	v_add_u32_e32 v223, 0x90000, v134
	v_add_u32_e32 v224, 0xa0000, v134
	v_add_u32_e32 v225, 0xb0000, v134
	v_add_u32_e32 v226, 0x8000, v134
	v_add_u32_e32 v227, 0x18000, v134
	v_add_u32_e32 v228, 0x28000, v134
	v_add_u32_e32 v229, 0x38000, v134
	v_add_u32_e32 v230, 0x88000, v134
	v_add_u32_e32 v231, 0x98000, v134
	v_add_u32_e32 v232, 0xa8000, v134
	v_add_u32_e32 v233, 0xb8000, v134
	global_load_dwordx4 v[142:145], v218, s[36:37] nt
	global_load_dwordx4 v[146:149], v226, s[36:37] nt
	global_load_dwordx4 v[156:159], v218, s[36:37] offset:512 nt
	global_load_dwordx4 v[160:163], v226, s[36:37] offset:512 nt
	global_load_dwordx4 v[164:167], v219, s[36:37] nt
	global_load_dwordx4 v[168:171], v227, s[36:37] nt
	global_load_dwordx4 v[172:175], v219, s[36:37] offset:512 nt
	global_load_dwordx4 v[176:179], v227, s[36:37] offset:512 nt
	global_load_dwordx4 v[180:183], v220, s[36:37] nt
	global_load_dwordx4 v[184:187], v228, s[36:37] nt
	global_load_dwordx4 v[188:191], v220, s[36:37] offset:512 nt
	global_load_dwordx4 v[192:195], v228, s[36:37] offset:512 nt
	global_load_dwordx4 v[196:199], v221, s[36:37] nt
	global_load_dwordx4 v[200:203], v229, s[36:37] nt
	global_load_dwordx4 v[204:207], v221, s[36:37] offset:512 nt
	global_load_dwordx4 v[208:211], v229, s[36:37] offset:512 nt
	v_cndmask_b32_e64 v234, v120, v124, s[94:95]
	v_cndmask_b32_e64 v235, v121, v125, s[94:95]
	v_cndmask_b32_e64 v236, v122, v126, s[94:95]
	v_cndmask_b32_e64 v237, v123, v127, s[94:95]
	v_mov_b32_dpp v238, v234 row_ror:8 row_mask:0xf bank_mask:0xf bound_ctrl:1
	v_mov_b32_dpp v239, v235 row_ror:8 row_mask:0xf bank_mask:0xf bound_ctrl:1
	v_mov_b32_dpp v240, v236 row_ror:8 row_mask:0xf bank_mask:0xf bound_ctrl:1
	v_mov_b32_dpp v241, v237 row_ror:8 row_mask:0xf bank_mask:0xf bound_ctrl:1
	v_cndmask_b32_e64 v124, v124, v238, s[94:95]
	v_cndmask_b32_e64 v125, v125, v239, s[94:95]
	v_cndmask_b32_e64 v126, v126, v240, s[94:95]
	v_cndmask_b32_e64 v127, v127, v241, s[94:95]
	v_cndmask_b32_e64 v120, v238, v120, s[94:95]
	v_cndmask_b32_e64 v121, v239, v121, s[94:95]
	v_cndmask_b32_e64 v122, v240, v122, s[94:95]
	v_cndmask_b32_e64 v123, v241, v123, s[94:95]
	s_waitcnt vmcnt(15)
	v_pk_add_f32 v[124:125], v[124:125], v[142:143]
	v_pk_add_f32 v[126:127], v[126:127], v[144:145]
	global_store_dwordx4 v218, v[124:127], s[50:51]
	global_load_dwordx4 v[142:145], v222, s[36:37] nt
	s_waitcnt vmcnt(16)
	v_pk_add_f32 v[120:121], v[120:121], v[146:147]
	v_pk_add_f32 v[122:123], v[122:123], v[148:149]
	global_store_dwordx4 v226, v[120:123], s[50:51]
	global_load_dwordx4 v[146:149], v230, s[36:37] nt
	v_cndmask_b32_e64 v234, v104, v116, s[94:95]
	v_cndmask_b32_e64 v235, v105, v117, s[94:95]
	v_cndmask_b32_e64 v236, v106, v118, s[94:95]
	v_cndmask_b32_e64 v237, v107, v119, s[94:95]
	v_mov_b32_dpp v238, v234 row_ror:8 row_mask:0xf bank_mask:0xf bound_ctrl:1
	v_mov_b32_dpp v239, v235 row_ror:8 row_mask:0xf bank_mask:0xf bound_ctrl:1
	v_mov_b32_dpp v240, v236 row_ror:8 row_mask:0xf bank_mask:0xf bound_ctrl:1
	v_mov_b32_dpp v241, v237 row_ror:8 row_mask:0xf bank_mask:0xf bound_ctrl:1
	v_cndmask_b32_e64 v116, v116, v238, s[94:95]
	v_cndmask_b32_e64 v117, v117, v239, s[94:95]
	v_cndmask_b32_e64 v118, v118, v240, s[94:95]
	v_cndmask_b32_e64 v119, v119, v241, s[94:95]
	v_cndmask_b32_e64 v104, v238, v104, s[94:95]
	v_cndmask_b32_e64 v105, v239, v105, s[94:95]
	v_cndmask_b32_e64 v106, v240, v106, s[94:95]
	v_cndmask_b32_e64 v107, v241, v107, s[94:95]
	s_waitcnt vmcnt(17)
	v_pk_add_f32 v[116:117], v[116:117], v[156:157]
	v_pk_add_f32 v[118:119], v[118:119], v[158:159]
	global_store_dwordx4 v218, v[116:119], s[50:51] offset:512
	global_load_dwordx4 v[156:159], v222, s[36:37] offset:512 nt
	s_waitcnt vmcnt(18)
	v_pk_add_f32 v[104:105], v[104:105], v[160:161]
	v_pk_add_f32 v[106:107], v[106:107], v[162:163]
	global_store_dwordx4 v226, v[104:107], s[50:51] offset:512
	global_load_dwordx4 v[160:163], v230, s[36:37] offset:512 nt
	v_cndmask_b32_e64 v234, v108, v112, s[94:95]
	v_cndmask_b32_e64 v235, v109, v113, s[94:95]
	v_cndmask_b32_e64 v236, v110, v114, s[94:95]
	v_cndmask_b32_e64 v237, v111, v115, s[94:95]
	v_mov_b32_dpp v238, v234 row_ror:8 row_mask:0xf bank_mask:0xf bound_ctrl:1
	v_mov_b32_dpp v239, v235 row_ror:8 row_mask:0xf bank_mask:0xf bound_ctrl:1
	v_mov_b32_dpp v240, v236 row_ror:8 row_mask:0xf bank_mask:0xf bound_ctrl:1
	v_mov_b32_dpp v241, v237 row_ror:8 row_mask:0xf bank_mask:0xf bound_ctrl:1
	v_cndmask_b32_e64 v112, v112, v238, s[94:95]
	v_cndmask_b32_e64 v113, v113, v239, s[94:95]
	v_cndmask_b32_e64 v114, v114, v240, s[94:95]
	v_cndmask_b32_e64 v115, v115, v241, s[94:95]
	v_cndmask_b32_e64 v108, v238, v108, s[94:95]
	v_cndmask_b32_e64 v109, v239, v109, s[94:95]
	v_cndmask_b32_e64 v110, v240, v110, s[94:95]
	v_cndmask_b32_e64 v111, v241, v111, s[94:95]
	s_waitcnt vmcnt(19)
	v_pk_add_f32 v[112:113], v[112:113], v[164:165]
	v_pk_add_f32 v[114:115], v[114:115], v[166:167]
	global_store_dwordx4 v219, v[112:115], s[50:51]
	global_load_dwordx4 v[164:167], v223, s[36:37] nt
	s_waitcnt vmcnt(20)
;     __device__ __forceinline__ void operator()(const pg8::f32x4 (&acc)[2][2][4][2], const pg8::Unit& u, int wr, int wc, int fr, int fq) const {
;         const int row0 = u.pm * 256 + wr * 64 + fr, col0 = u.pn * 256 + wc * 32 + 4 * fq;
; #pragma unroll
;         for (int ai = 0; ai < 2; ++ai)
; #pragma unroll
;             for (int m = 0; m < 4; ++m) { const size_t off = (size_t)(row0 + ai * 128 + m * 16) * DM + col0;
; #pragma unroll
;                 for (int bj = 0; bj < 2; ++bj)
; #pragma unroll
;                     for (int n = 0; n < 2; ++n) { const size_t o2 = off + bj * 128 + n * 16; *(pg8::f32x4*)(out + o2) = *(const pg8::f32x4*)(x + o2) + acc[ai][bj][m][n]; }
;                 if (m & 1) asm volatile("" ::: "memory"); }
	v_pk_add_f32 v[108:109], v[108:109], v[168:169]
	v_pk_add_f32 v[110:111], v[110:111], v[170:171]
	global_store_dwordx4 v227, v[108:111], s[50:51]
	global_load_dwordx4 v[168:171], v231, s[36:37] nt
	v_cndmask_b32_e64 v234, v88, v100, s[94:95]
	v_cndmask_b32_e64 v235, v89, v101, s[94:95]
	v_cndmask_b32_e64 v236, v90, v102, s[94:95]
	v_cndmask_b32_e64 v237, v91, v103, s[94:95]
	v_mov_b32_dpp v238, v234 row_ror:8 row_mask:0xf bank_mask:0xf bound_ctrl:1
	v_mov_b32_dpp v239, v235 row_ror:8 row_mask:0xf bank_mask:0xf bound_ctrl:1
	v_mov_b32_dpp v240, v236 row_ror:8 row_mask:0xf bank_mask:0xf bound_ctrl:1
	v_mov_b32_dpp v241, v237 row_ror:8 row_mask:0xf bank_mask:0xf bound_ctrl:1
	v_cndmask_b32_e64 v100, v100, v238, s[94:95]
	v_cndmask_b32_e64 v101, v101, v239, s[94:95]
	v_cndmask_b32_e64 v102, v102, v240, s[94:95]
	v_cndmask_b32_e64 v103, v103, v241, s[94:95]
	v_cndmask_b32_e64 v88, v238, v88, s[94:95]
	v_cndmask_b32_e64 v89, v239, v89, s[94:95]
	v_cndmask_b32_e64 v90, v240, v90, s[94:95]
	v_cndmask_b32_e64 v91, v241, v91, s[94:95]
	s_waitcnt vmcnt(21)
	v_pk_add_f32 v[100:101], v[100:101], v[172:173]
	v_pk_add_f32 v[102:103], v[102:103], v[174:175]
	global_store_dwordx4 v219, v[100:103], s[50:51] offset:512
	global_load_dwordx4 v[172:175], v223, s[36:37] offset:512 nt
	s_waitcnt vmcnt(22)
	v_pk_add_f32 v[88:89], v[88:89], v[176:177]
	v_pk_add_f32 v[90:91], v[90:91], v[178:179]
	global_store_dwordx4 v227, v[88:91], s[50:51] offset:512
	global_load_dwordx4 v[176:179], v231, s[36:37] offset:512 nt
	v_cndmask_b32_e64 v234, v92, v96, s[94:95]
	v_cndmask_b32_e64 v235, v93, v97, s[94:95]
	v_cndmask_b32_e64 v236, v94, v98, s[94:95]
	v_cndmask_b32_e64 v237, v95, v99, s[94:95]
	v_mov_b32_dpp v238, v234 row_ror:8 row_mask:0xf bank_mask:0xf bound_ctrl:1
	v_mov_b32_dpp v239, v235 row_ror:8 row_mask:0xf bank_mask:0xf bound_ctrl:1
	v_mov_b32_dpp v240, v236 row_ror:8 row_mask:0xf bank_mask:0xf bound_ctrl:1
	v_mov_b32_dpp v241, v237 row_ror:8 row_mask:0xf bank_mask:0xf bound_ctrl:1
	v_cndmask_b32_e64 v96, v96, v238, s[94:95]
	v_cndmask_b32_e64 v97, v97, v239, s[94:95]
	v_cndmask_b32_e64 v98, v98, v240, s[94:95]
	v_cndmask_b32_e64 v99, v99, v241, s[94:95]
	v_cndmask_b32_e64 v92, v238, v92, s[94:95]
	v_cndmask_b32_e64 v93, v239, v93, s[94:95]
	v_cndmask_b32_e64 v94, v240, v94, s[94:95]
	v_cndmask_b32_e64 v95, v241, v95, s[94:95]
	s_waitcnt vmcnt(23)
	v_pk_add_f32 v[96:97], v[96:97], v[180:181]
	v_pk_add_f32 v[98:99], v[98:99], v[182:183]
	global_store_dwordx4 v220, v[96:99], s[50:51]
	global_load_dwordx4 v[180:183], v224, s[36:37] nt
	s_waitcnt vmcnt(24)
	v_pk_add_f32 v[92:93], v[92:93], v[184:185]
	v_pk_add_f32 v[94:95], v[94:95], v[186:187]
	global_store_dwordx4 v228, v[92:95], s[50:51]
	global_load_dwordx4 v[184:187], v232, s[36:37] nt
	v_cndmask_b32_e64 v234, v72, v84, s[94:95]
	v_cndmask_b32_e64 v235, v73, v85, s[94:95]
	v_cndmask_b32_e64 v236, v74, v86, s[94:95]
	v_cndmask_b32_e64 v237, v75, v87, s[94:95]
	v_mov_b32_dpp v238, v234 row_ror:8 row_mask:0xf bank_mask:0xf bound_ctrl:1
	v_mov_b32_dpp v239, v235 row_ror:8 row_mask:0xf bank_mask:0xf bound_ctrl:1
	v_mov_b32_dpp v240, v236 row_ror:8 row_mask:0xf bank_mask:0xf bound_ctrl:1
	v_mov_b32_dpp v241, v237 row_ror:8 row_mask:0xf bank_mask:0xf bound_ctrl:1
	v_cndmask_b32_e64 v84, v84, v238, s[94:95]
	v_cndmask_b32_e64 v85, v85, v239, s[94:95]
	v_cndmask_b32_e64 v86, v86, v240, s[94:95]
	v_cndmask_b32_e64 v87, v87, v241, s[94:95]
	v_cndmask_b32_e64 v72, v238, v72, s[94:95]
	v_cndmask_b32_e64 v73, v239, v73, s[94:95]
	v_cndmask_b32_e64 v74, v240, v74, s[94:95]
	v_cndmask_b32_e64 v75, v241, v75, s[94:95]
	s_waitcnt vmcnt(25)
	v_pk_add_f32 v[84:85], v[84:85], v[188:189]
	v_pk_add_f32 v[86:87], v[86:87], v[190:191]
	global_store_dwordx4 v220, v[84:87], s[50:51] offset:512
	global_load_dwordx4 v[188:191], v224, s[36:37] offset:512 nt
	s_waitcnt vmcnt(26)
	v_pk_add_f32 v[72:73], v[72:73], v[192:193]
	v_pk_add_f32 v[74:75], v[74:75], v[194:195]
	global_store_dwordx4 v228, v[72:75], s[50:51] offset:512
	global_load_dwordx4 v[192:195], v232, s[36:37] offset:512 nt
	v_cndmask_b32_e64 v234, v76, v80, s[94:95]
	v_cndmask_b32_e64 v235, v77, v81, s[94:95]
	v_cndmask_b32_e64 v236, v78, v82, s[94:95]
	v_cndmask_b32_e64 v237, v79, v83, s[94:95]
	v_mov_b32_dpp v238, v234 row_ror:8 row_mask:0xf bank_mask:0xf bound_ctrl:1
	v_mov_b32_dpp v239, v235 row_ror:8 row_mask:0xf bank_mask:0xf bound_ctrl:1
	v_mov_b32_dpp v240, v236 row_ror:8 row_mask:0xf bank_mask:0xf bound_ctrl:1
	v_mov_b32_dpp v241, v237 row_ror:8 row_mask:0xf bank_mask:0xf bound_ctrl:1
	v_cndmask_b32_e64 v80, v80, v238, s[94:95]
	v_cndmask_b32_e64 v81, v81, v239, s[94:95]
	v_cndmask_b32_e64 v82, v82, v240, s[94:95]
	v_cndmask_b32_e64 v83, v83, v241, s[94:95]
	v_cndmask_b32_e64 v76, v238, v76, s[94:95]
	v_cndmask_b32_e64 v77, v239, v77, s[94:95]
	v_cndmask_b32_e64 v78, v240, v78, s[94:95]
	v_cndmask_b32_e64 v79, v241, v79, s[94:95]
	s_waitcnt vmcnt(27)
	v_pk_add_f32 v[80:81], v[80:81], v[196:197]
	v_pk_add_f32 v[82:83], v[82:83], v[198:199]
	global_store_dwordx4 v221, v[80:83], s[50:51]
	global_load_dwordx4 v[196:199], v225, s[36:37] nt
	s_waitcnt vmcnt(28)
;     __device__ __forceinline__ void operator()(const pg8::f32x4 (&acc)[2][2][4][2], const pg8::Unit& u, int wr, int wc, int fr, int fq) const {
;         const int row0 = u.pm * 256 + wr * 64 + fr, col0 = u.pn * 256 + wc * 32 + 4 * fq;
; #pragma unroll
;         for (int ai = 0; ai < 2; ++ai)
; #pragma unroll
;             for (int m = 0; m < 4; ++m) { const size_t off = (size_t)(row0 + ai * 128 + m * 16) * DM + col0;
; #pragma unroll
;                 for (int bj = 0; bj < 2; ++bj)
; #pragma unroll
;                     for (int n = 0; n < 2; ++n) { const size_t o2 = off + bj * 128 + n * 16; *(pg8::f32x4*)(out + o2) = *(const pg8::f32x4*)(x + o2) + acc[ai][bj][m][n]; }
;                 if (m & 1) asm volatile("" ::: "memory"); }
	v_pk_add_f32 v[76:77], v[76:77], v[200:201]
	v_pk_add_f32 v[78:79], v[78:79], v[202:203]
	global_store_dwordx4 v229, v[76:79], s[50:51]
	global_load_dwordx4 v[200:203], v233, s[36:37] nt
	v_cndmask_b32_e64 v234, v64, v68, s[94:95]
	v_cndmask_b32_e64 v235, v65, v69, s[94:95]
	v_cndmask_b32_e64 v236, v66, v70, s[94:95]
	v_cndmask_b32_e64 v237, v67, v71, s[94:95]
	v_mov_b32_dpp v238, v234 row_ror:8 row_mask:0xf bank_mask:0xf bound_ctrl:1
	v_mov_b32_dpp v239, v235 row_ror:8 row_mask:0xf bank_mask:0xf bound_ctrl:1
	v_mov_b32_dpp v240, v236 row_ror:8 row_mask:0xf bank_mask:0xf bound_ctrl:1
	v_mov_b32_dpp v241, v237 row_ror:8 row_mask:0xf bank_mask:0xf bound_ctrl:1
	v_cndmask_b32_e64 v68, v68, v238, s[94:95]
	v_cndmask_b32_e64 v69, v69, v239, s[94:95]
	v_cndmask_b32_e64 v70, v70, v240, s[94:95]
	v_cndmask_b32_e64 v71, v71, v241, s[94:95]
	v_cndmask_b32_e64 v64, v238, v64, s[94:95]
	v_cndmask_b32_e64 v65, v239, v65, s[94:95]
	v_cndmask_b32_e64 v66, v240, v66, s[94:95]
	v_cndmask_b32_e64 v67, v241, v67, s[94:95]
	s_waitcnt vmcnt(29)
	v_pk_add_f32 v[68:69], v[68:69], v[204:205]
	v_pk_add_f32 v[70:71], v[70:71], v[206:207]
	global_store_dwordx4 v221, v[68:71], s[50:51] offset:512
	global_load_dwordx4 v[204:207], v225, s[36:37] offset:512 nt
	s_waitcnt vmcnt(30)
	v_pk_add_f32 v[64:65], v[64:65], v[208:209]
	v_pk_add_f32 v[66:67], v[66:67], v[210:211]
	global_store_dwordx4 v229, v[64:67], s[50:51] offset:512
	global_load_dwordx4 v[208:211], v233, s[36:37] offset:512 nt
	v_cndmask_b32_e64 v234, v56, v60, s[94:95]
	v_cndmask_b32_e64 v235, v57, v61, s[94:95]
	v_cndmask_b32_e64 v236, v58, v62, s[94:95]
	v_cndmask_b32_e64 v237, v59, v63, s[94:95]
	v_mov_b32_dpp v238, v234 row_ror:8 row_mask:0xf bank_mask:0xf bound_ctrl:1
	v_mov_b32_dpp v239, v235 row_ror:8 row_mask:0xf bank_mask:0xf bound_ctrl:1
	v_mov_b32_dpp v240, v236 row_ror:8 row_mask:0xf bank_mask:0xf bound_ctrl:1
	v_mov_b32_dpp v241, v237 row_ror:8 row_mask:0xf bank_mask:0xf bound_ctrl:1
	v_cndmask_b32_e64 v60, v60, v238, s[94:95]
	v_cndmask_b32_e64 v61, v61, v239, s[94:95]
	v_cndmask_b32_e64 v62, v62, v240, s[94:95]
	v_cndmask_b32_e64 v63, v63, v241, s[94:95]
	v_cndmask_b32_e64 v56, v238, v56, s[94:95]
	v_cndmask_b32_e64 v57, v239, v57, s[94:95]
	v_cndmask_b32_e64 v58, v240, v58, s[94:95]
	v_cndmask_b32_e64 v59, v241, v59, s[94:95]
	s_waitcnt vmcnt(30)
	v_pk_add_f32 v[60:61], v[60:61], v[142:143]
	v_pk_add_f32 v[62:63], v[62:63], v[144:145]
	global_store_dwordx4 v222, v[60:63], s[50:51]
	s_waitcnt vmcnt(29)
	v_pk_add_f32 v[56:57], v[56:57], v[146:147]
	v_pk_add_f32 v[58:59], v[58:59], v[148:149]
	global_store_dwordx4 v230, v[56:59], s[50:51]
	v_cndmask_b32_e64 v234, v40, v52, s[94:95]
	v_cndmask_b32_e64 v235, v41, v53, s[94:95]
	v_cndmask_b32_e64 v236, v42, v54, s[94:95]
	v_cndmask_b32_e64 v237, v43, v55, s[94:95]
	v_mov_b32_dpp v238, v234 row_ror:8 row_mask:0xf bank_mask:0xf bound_ctrl:1
	v_mov_b32_dpp v239, v235 row_ror:8 row_mask:0xf bank_mask:0xf bound_ctrl:1
	v_mov_b32_dpp v240, v236 row_ror:8 row_mask:0xf bank_mask:0xf bound_ctrl:1
	v_mov_b32_dpp v241, v237 row_ror:8 row_mask:0xf bank_mask:0xf bound_ctrl:1
	v_cndmask_b32_e64 v52, v52, v238, s[94:95]
	v_cndmask_b32_e64 v53, v53, v239, s[94:95]
	v_cndmask_b32_e64 v54, v54, v240, s[94:95]
	v_cndmask_b32_e64 v55, v55, v241, s[94:95]
	v_cndmask_b32_e64 v40, v238, v40, s[94:95]
	v_cndmask_b32_e64 v41, v239, v41, s[94:95]
	v_cndmask_b32_e64 v42, v240, v42, s[94:95]
	v_cndmask_b32_e64 v43, v241, v43, s[94:95]
	s_waitcnt vmcnt(28)
	v_pk_add_f32 v[52:53], v[52:53], v[156:157]
	v_pk_add_f32 v[54:55], v[54:55], v[158:159]
	global_store_dwordx4 v222, v[52:55], s[50:51] offset:512
	s_waitcnt vmcnt(27)
	v_pk_add_f32 v[40:41], v[40:41], v[160:161]
	v_pk_add_f32 v[42:43], v[42:43], v[162:163]
	global_store_dwordx4 v230, v[40:43], s[50:51] offset:512
	v_cndmask_b32_e64 v234, v44, v48, s[94:95]
	v_cndmask_b32_e64 v235, v45, v49, s[94:95]
	v_cndmask_b32_e64 v236, v46, v50, s[94:95]
	v_cndmask_b32_e64 v237, v47, v51, s[94:95]
	v_mov_b32_dpp v238, v234 row_ror:8 row_mask:0xf bank_mask:0xf bound_ctrl:1
	v_mov_b32_dpp v239, v235 row_ror:8 row_mask:0xf bank_mask:0xf bound_ctrl:1
	v_mov_b32_dpp v240, v236 row_ror:8 row_mask:0xf bank_mask:0xf bound_ctrl:1
	v_mov_b32_dpp v241, v237 row_ror:8 row_mask:0xf bank_mask:0xf bound_ctrl:1
	v_cndmask_b32_e64 v48, v48, v238, s[94:95]
	v_cndmask_b32_e64 v49, v49, v239, s[94:95]
	v_cndmask_b32_e64 v50, v50, v240, s[94:95]
	v_cndmask_b32_e64 v51, v51, v241, s[94:95]
	v_cndmask_b32_e64 v44, v238, v44, s[94:95]
	v_cndmask_b32_e64 v45, v239, v45, s[94:95]
	v_cndmask_b32_e64 v46, v240, v46, s[94:95]
	v_cndmask_b32_e64 v47, v241, v47, s[94:95]
	s_waitcnt vmcnt(26)
	v_pk_add_f32 v[48:49], v[48:49], v[164:165]
	v_pk_add_f32 v[50:51], v[50:51], v[166:167]
	global_store_dwordx4 v223, v[48:51], s[50:51]
	s_waitcnt vmcnt(25)
	v_pk_add_f32 v[44:45], v[44:45], v[168:169]
	v_pk_add_f32 v[46:47], v[46:47], v[170:171]
	global_store_dwordx4 v231, v[44:47], s[50:51]
	v_cndmask_b32_e64 v234, v24, v36, s[94:95]
	v_cndmask_b32_e64 v235, v25, v37, s[94:95]
	v_cndmask_b32_e64 v236, v26, v38, s[94:95]
	v_cndmask_b32_e64 v237, v27, v39, s[94:95]
	v_mov_b32_dpp v238, v234 row_ror:8 row_mask:0xf bank_mask:0xf bound_ctrl:1
	v_mov_b32_dpp v239, v235 row_ror:8 row_mask:0xf bank_mask:0xf bound_ctrl:1
	v_mov_b32_dpp v240, v236 row_ror:8 row_mask:0xf bank_mask:0xf bound_ctrl:1
	v_mov_b32_dpp v241, v237 row_ror:8 row_mask:0xf bank_mask:0xf bound_ctrl:1
	v_cndmask_b32_e64 v36, v36, v238, s[94:95]
	v_cndmask_b32_e64 v37, v37, v239, s[94:95]
	v_cndmask_b32_e64 v38, v38, v240, s[94:95]
	v_cndmask_b32_e64 v39, v39, v241, s[94:95]
	v_cndmask_b32_e64 v24, v238, v24, s[94:95]
	v_cndmask_b32_e64 v25, v239, v25, s[94:95]
	v_cndmask_b32_e64 v26, v240, v26, s[94:95]
	v_cndmask_b32_e64 v27, v241, v27, s[94:95]
	s_waitcnt vmcnt(24)
;     __device__ __forceinline__ void operator()(const pg8::f32x4 (&acc)[2][2][4][2], const pg8::Unit& u, int wr, int wc, int fr, int fq) const {
;         const int row0 = u.pm * 256 + wr * 64 + fr, col0 = u.pn * 256 + wc * 32 + 4 * fq;
; #pragma unroll
;         for (int ai = 0; ai < 2; ++ai)
; #pragma unroll
;             for (int m = 0; m < 4; ++m) { const size_t off = (size_t)(row0 + ai * 128 + m * 16) * DM + col0;
; #pragma unroll
;                 for (int bj = 0; bj < 2; ++bj)
; #pragma unroll
;                     for (int n = 0; n < 2; ++n) { const size_t o2 = off + bj * 128 + n * 16; *(pg8::f32x4*)(out + o2) = *(const pg8::f32x4*)(x + o2) + acc[ai][bj][m][n]; }
;                 if (m & 1) asm volatile("" ::: "memory"); }
	v_pk_add_f32 v[36:37], v[36:37], v[172:173]
	v_pk_add_f32 v[38:39], v[38:39], v[174:175]
	global_store_dwordx4 v223, v[36:39], s[50:51] offset:512
	s_waitcnt vmcnt(23)
	v_pk_add_f32 v[24:25], v[24:25], v[176:177]
	v_pk_add_f32 v[26:27], v[26:27], v[178:179]
	global_store_dwordx4 v231, v[24:27], s[50:51] offset:512
	v_cndmask_b32_e64 v234, v28, v32, s[94:95]
	v_cndmask_b32_e64 v235, v29, v33, s[94:95]
	v_cndmask_b32_e64 v236, v30, v34, s[94:95]
	v_cndmask_b32_e64 v237, v31, v35, s[94:95]
	v_mov_b32_dpp v238, v234 row_ror:8 row_mask:0xf bank_mask:0xf bound_ctrl:1
	v_mov_b32_dpp v239, v235 row_ror:8 row_mask:0xf bank_mask:0xf bound_ctrl:1
	v_mov_b32_dpp v240, v236 row_ror:8 row_mask:0xf bank_mask:0xf bound_ctrl:1
	v_mov_b32_dpp v241, v237 row_ror:8 row_mask:0xf bank_mask:0xf bound_ctrl:1
	v_cndmask_b32_e64 v32, v32, v238, s[94:95]
	v_cndmask_b32_e64 v33, v33, v239, s[94:95]
	v_cndmask_b32_e64 v34, v34, v240, s[94:95]
	v_cndmask_b32_e64 v35, v35, v241, s[94:95]
	v_cndmask_b32_e64 v28, v238, v28, s[94:95]
	v_cndmask_b32_e64 v29, v239, v29, s[94:95]
	v_cndmask_b32_e64 v30, v240, v30, s[94:95]
	v_cndmask_b32_e64 v31, v241, v31, s[94:95]
	s_waitcnt vmcnt(22)
	v_pk_add_f32 v[32:33], v[32:33], v[180:181]
	v_pk_add_f32 v[34:35], v[34:35], v[182:183]
	global_store_dwordx4 v224, v[32:35], s[50:51]
	s_waitcnt vmcnt(21)
	v_pk_add_f32 v[28:29], v[28:29], v[184:185]
	v_pk_add_f32 v[30:31], v[30:31], v[186:187]
	global_store_dwordx4 v232, v[28:31], s[50:51]
	v_cndmask_b32_e64 v234, v8, v20, s[94:95]
	v_cndmask_b32_e64 v235, v9, v21, s[94:95]
	v_cndmask_b32_e64 v236, v10, v22, s[94:95]
	v_cndmask_b32_e64 v237, v11, v23, s[94:95]
	v_mov_b32_dpp v238, v234 row_ror:8 row_mask:0xf bank_mask:0xf bound_ctrl:1
	v_mov_b32_dpp v239, v235 row_ror:8 row_mask:0xf bank_mask:0xf bound_ctrl:1
	v_mov_b32_dpp v240, v236 row_ror:8 row_mask:0xf bank_mask:0xf bound_ctrl:1
	v_mov_b32_dpp v241, v237 row_ror:8 row_mask:0xf bank_mask:0xf bound_ctrl:1
	v_cndmask_b32_e64 v20, v20, v238, s[94:95]
	v_cndmask_b32_e64 v21, v21, v239, s[94:95]
	v_cndmask_b32_e64 v22, v22, v240, s[94:95]
	v_cndmask_b32_e64 v23, v23, v241, s[94:95]
	v_cndmask_b32_e64 v8, v238, v8, s[94:95]
	v_cndmask_b32_e64 v9, v239, v9, s[94:95]
	v_cndmask_b32_e64 v10, v240, v10, s[94:95]
	v_cndmask_b32_e64 v11, v241, v11, s[94:95]
	s_waitcnt vmcnt(20)
	v_pk_add_f32 v[20:21], v[20:21], v[188:189]
	v_pk_add_f32 v[22:23], v[22:23], v[190:191]
	global_store_dwordx4 v224, v[20:23], s[50:51] offset:512
	s_waitcnt vmcnt(19)
	v_pk_add_f32 v[8:9], v[8:9], v[192:193]
	v_pk_add_f32 v[10:11], v[10:11], v[194:195]
	global_store_dwordx4 v232, v[8:11], s[50:51] offset:512
	v_cndmask_b32_e64 v234, v12, v16, s[94:95]
	v_cndmask_b32_e64 v235, v13, v17, s[94:95]
	v_cndmask_b32_e64 v236, v14, v18, s[94:95]
	v_cndmask_b32_e64 v237, v15, v19, s[94:95]
	v_mov_b32_dpp v238, v234 row_ror:8 row_mask:0xf bank_mask:0xf bound_ctrl:1
	v_mov_b32_dpp v239, v235 row_ror:8 row_mask:0xf bank_mask:0xf bound_ctrl:1
	v_mov_b32_dpp v240, v236 row_ror:8 row_mask:0xf bank_mask:0xf bound_ctrl:1
	v_mov_b32_dpp v241, v237 row_ror:8 row_mask:0xf bank_mask:0xf bound_ctrl:1
	v_cndmask_b32_e64 v16, v16, v238, s[94:95]
	v_cndmask_b32_e64 v17, v17, v239, s[94:95]
	v_cndmask_b32_e64 v18, v18, v240, s[94:95]
	v_cndmask_b32_e64 v19, v19, v241, s[94:95]
	v_cndmask_b32_e64 v12, v238, v12, s[94:95]
	v_cndmask_b32_e64 v13, v239, v13, s[94:95]
	v_cndmask_b32_e64 v14, v240, v14, s[94:95]
	v_cndmask_b32_e64 v15, v241, v15, s[94:95]
	s_waitcnt vmcnt(18)
	v_pk_add_f32 v[16:17], v[16:17], v[196:197]
	v_pk_add_f32 v[18:19], v[18:19], v[198:199]
	global_store_dwordx4 v225, v[16:19], s[50:51]
	s_waitcnt vmcnt(17)
	v_pk_add_f32 v[12:13], v[12:13], v[200:201]
	v_pk_add_f32 v[14:15], v[14:15], v[202:203]
	global_store_dwordx4 v233, v[12:15], s[50:51]
	v_cndmask_b32_e64 v234, v0, v4, s[94:95]
	v_cndmask_b32_e64 v235, v1, v5, s[94:95]
	v_cndmask_b32_e64 v236, v2, v6, s[94:95]
	v_cndmask_b32_e64 v237, v3, v7, s[94:95]
	v_mov_b32_dpp v238, v234 row_ror:8 row_mask:0xf bank_mask:0xf bound_ctrl:1
	v_mov_b32_dpp v239, v235 row_ror:8 row_mask:0xf bank_mask:0xf bound_ctrl:1
	v_mov_b32_dpp v240, v236 row_ror:8 row_mask:0xf bank_mask:0xf bound_ctrl:1
	v_mov_b32_dpp v241, v237 row_ror:8 row_mask:0xf bank_mask:0xf bound_ctrl:1
	v_cndmask_b32_e64 v4, v4, v238, s[94:95]
	v_cndmask_b32_e64 v5, v5, v239, s[94:95]
	v_cndmask_b32_e64 v6, v6, v240, s[94:95]
	v_cndmask_b32_e64 v7, v7, v241, s[94:95]
	v_cndmask_b32_e64 v0, v238, v0, s[94:95]
	v_cndmask_b32_e64 v1, v239, v1, s[94:95]
	v_cndmask_b32_e64 v2, v240, v2, s[94:95]
	v_cndmask_b32_e64 v3, v241, v3, s[94:95]
	s_waitcnt vmcnt(16)
	v_pk_add_f32 v[4:5], v[4:5], v[204:205]
	v_pk_add_f32 v[6:7], v[6:7], v[206:207]
	global_store_dwordx4 v225, v[4:7], s[50:51] offset:512
	s_waitcnt vmcnt(15)
	v_pk_add_f32 v[0:1], v[0:1], v[208:209]
	v_pk_add_f32 v[2:3], v[2:3], v[210:211]
	global_store_dwordx4 v233, v[0:3], s[50:51] offset:512
	s_cbranch_vccnz .LBB0_469
	s_andn2_b64 vcc, exec, s[0:1]
	s_cbranch_vccnz .LBB0_468
	s_barrier
	s_branch .LBB0_468
